# pass2 steps (2)+(3) merged: Qb fragments shared between o_inter and the intra-chunk scores, all operands via single ds_read_b64 two k-steps ahead; on top of v5
# speedup vs baseline: 1.0051x; 1.0008x over previous
.LBB0_1334:
	s_mul_i32 s22, s22, 0xe400
	s_add_i32 s27, s22, 0
	v_add3_u32 v147, s27, v104, v109
	s_add_i32 s29, s27, s19
	ds_read_b64 v[148:149], v147
	ds_read_b64 v[150:151], v147 offset:32
	ds_read_b64 v[152:153], v147 offset:4352
	ds_read_b64 v[154:155], v147 offset:4384
	ds_read_b64 v[196:197], v147 offset:8704
	ds_read_b64 v[198:199], v147 offset:8736
	ds_read_b64 v[200:201], v147 offset:13056
	ds_read_b64 v[202:203], v147 offset:13088
	v_cvt_pk_bf16_f32 v126, v26, v27
	v_cvt_pk_bf16_f32 v127, v28, v29
	v_cvt_pk_bf16_f32 v128, v30, v31
	v_cvt_pk_bf16_f32 v129, v32, v33
	ds_read_b64 v[156:157], v147 offset:64
	ds_read_b64 v[158:159], v147 offset:96
	ds_read_b64 v[160:161], v147 offset:4416
	ds_read_b64 v[162:163], v147 offset:4448
	ds_read_b64 v[204:205], v147 offset:8768
	ds_read_b64 v[206:207], v147 offset:8800
	s_waitcnt lgkmcnt(12)
	v_mfma_f32_16x16x32_bf16 v[62:65], v[148:151], v[126:129], 0
	ds_read_b64 v[208:209], v147 offset:13120
	ds_read_b64 v[210:211], v147 offset:13152
	v_cvt_pk_bf16_f32 v130, v34, v35
	v_cvt_pk_bf16_f32 v131, v36, v37
	v_cvt_pk_bf16_f32 v132, v38, v39
	v_cvt_pk_bf16_f32 v133, v40, v41
	s_waitcnt lgkmcnt(12)
	v_mfma_f32_16x16x32_bf16 v[58:61], v[152:155], v[126:129], 0
	s_waitcnt lgkmcnt(10)
	v_mfma_f32_16x16x32_bf16 v[164:167], v[196:199], v[148:151], 0
	v_mfma_f32_16x16x32_bf16 v[168:171], v[196:199], v[152:155], 0
	s_waitcnt lgkmcnt(8)
	v_mfma_f32_16x16x32_bf16 v[172:175], v[200:203], v[152:155], 0
	ds_read_b64 v[148:149], v147 offset:128
	ds_read_b64 v[150:151], v147 offset:160
	ds_read_b64 v[152:153], v147 offset:4480
	ds_read_b64 v[154:155], v147 offset:4512
	ds_read_b64 v[196:197], v147 offset:8832
	ds_read_b64 v[198:199], v147 offset:8864
	s_waitcnt lgkmcnt(12)
	v_mfma_f32_16x16x32_bf16 v[62:65], v[156:159], v[130:133], v[62:65]
	ds_read_b64 v[200:201], v147 offset:13184
	ds_read_b64 v[202:203], v147 offset:13216
	v_cvt_pk_bf16_f32 v134, v42, v43
	v_cvt_pk_bf16_f32 v135, v44, v45
	v_cvt_pk_bf16_f32 v136, v46, v47
	v_cvt_pk_bf16_f32 v137, v48, v49
	s_waitcnt lgkmcnt(12)
	v_mfma_f32_16x16x32_bf16 v[58:61], v[160:163], v[130:133], v[58:61]
	s_waitcnt lgkmcnt(10)
	v_mfma_f32_16x16x32_bf16 v[164:167], v[204:207], v[156:159], v[164:167]
	v_mfma_f32_16x16x32_bf16 v[168:171], v[204:207], v[160:163], v[168:171]
	s_waitcnt lgkmcnt(8)
	v_mfma_f32_16x16x32_bf16 v[172:175], v[208:211], v[160:163], v[172:175]
	ds_read_b64 v[156:157], v147 offset:192
	ds_read_b64 v[158:159], v147 offset:224
	ds_read_b64 v[160:161], v147 offset:4544
	ds_read_b64 v[162:163], v147 offset:4576
	ds_read_b64 v[204:205], v147 offset:8896
	ds_read_b64 v[206:207], v147 offset:8928
	s_waitcnt lgkmcnt(12)
	v_mfma_f32_16x16x32_bf16 v[62:65], v[148:151], v[134:137], v[62:65]
	ds_read_b64 v[208:209], v147 offset:13248
	ds_read_b64 v[210:211], v147 offset:13280
	v_cvt_pk_bf16_f32 v138, v50, v51
	v_cvt_pk_bf16_f32 v139, v52, v53
	v_cvt_pk_bf16_f32 v140, v54, v55
	v_cvt_pk_bf16_f32 v141, v56, v57
	s_waitcnt lgkmcnt(12)
	v_mfma_f32_16x16x32_bf16 v[58:61], v[152:155], v[134:137], v[58:61]
	s_waitcnt lgkmcnt(10)
	v_mfma_f32_16x16x32_bf16 v[164:167], v[196:199], v[148:151], v[164:167]
	v_mfma_f32_16x16x32_bf16 v[168:171], v[196:199], v[152:155], v[168:171]
	s_waitcnt lgkmcnt(8)
	v_mfma_f32_16x16x32_bf16 v[172:175], v[200:203], v[152:155], v[172:175]
	v_add_u32_e32 v176, s27, v106
	v_add_u32_e32 v68, v176, v123
	ds_read_b64_tr_b16 v[66:67], v68 offset:37888
	ds_read_b64_tr_b16 v[68:69], v68 offset:43008
	s_waitcnt lgkmcnt(8)
	v_mfma_f32_16x16x32_bf16 v[62:65], v[156:159], v[138:141], v[62:65]
	s_waitcnt lgkmcnt(6)
	v_mfma_f32_16x16x32_bf16 v[58:61], v[160:163], v[138:141], v[58:61]
	s_waitcnt lgkmcnt(4)
	v_mfma_f32_16x16x32_bf16 v[164:167], v[204:207], v[156:159], v[164:167]
	v_mfma_f32_16x16x32_bf16 v[168:171], v[204:207], v[160:163], v[168:171]
	s_waitcnt lgkmcnt(2)
	v_mfma_f32_16x16x32_bf16 v[172:175], v[208:211], v[160:163], v[172:175]
	v_add_u32_e32 v125, s27, v105
	v_add_u32_e32 v134, v176, v110
	v_mov_b32_e32 v177, s55
	v_mov_b32_e32 v72, v16
	v_mov_b32_e32 v73, v16
	s_nop 0
	v_cndmask_b32_e64 v165, 0, v165, s[6:7]
	v_cndmask_b32_e64 v166, v166, 0, s[8:9]
	v_cndmask_b32_e64 v167, v167, 0, s[10:11]
	v_cndmask_b32_e64 v164, v164, v177, s[4:5]
	v_cvt_pk_bf16_f32 v70, v164, v165
	v_cvt_pk_bf16_f32 v71, v166, v167
	v_cndmask_b32_e64 v172, v172, v177, s[4:5]
	v_cndmask_b32_e64 v173, v173, 0, s[12:13]
	v_cndmask_b32_e64 v174, v174, 0, s[14:15]
	v_cndmask_b32_e64 v175, v175, 0, s[16:17]
	s_waitcnt lgkmcnt(0)
	v_mfma_f32_16x16x32_bf16 v[62:65], v[70:73], v[66:69], v[62:65]
	v_cvt_pk_bf16_f32 v70, v168, v169
	v_cvt_pk_bf16_f32 v71, v170, v171
	v_cvt_pk_bf16_f32 v72, v172, v173
	v_cvt_pk_bf16_f32 v73, v174, v175
	s_nop 1
	v_mfma_f32_16x16x32_bf16 v[58:61], v[70:73], v[66:69], v[58:61]
	ds_read_b128 v[70:73], v125 offset:56832
	ds_read_b64_tr_b16 v[128:129], v134 offset:32768
	ds_read_b64_tr_b16 v[126:127], v134 offset:27648
	ds_read_b64_tr_b16 v[130:131], v134 offset:27680
	s_waitcnt lgkmcnt(3)
	v_pk_mul_f32 v[26:27], v[26:27], v[70:71]
	v_add_u32_e32 v70, s27, v111
	v_pk_mul_f32 v[28:29], v[28:29], v[72:73]
	ds_read_b128 v[70:73], v70 offset:56832
	ds_read_b64_tr_b16 v[132:133], v134 offset:32800
	s_waitcnt lgkmcnt(3)
	v_mfma_f32_16x16x32_bf16 v[26:29], v[126:129], v[66:69], v[26:29]
	s_waitcnt lgkmcnt(1)
	v_pk_mul_f32 v[32:33], v[32:33], v[72:73]
	v_pk_mul_f32 v[30:31], v[30:31], v[70:71]
	ds_read_b128 v[70:73], v125 offset:56960
	ds_read_b64_tr_b16 v[126:127], v134 offset:27712
	ds_read_b64_tr_b16 v[128:129], v134 offset:32832
	s_waitcnt lgkmcnt(3)
	v_mfma_f32_16x16x32_bf16 v[30:33], v[130:133], v[66:69], v[30:33]
	s_waitcnt lgkmcnt(2)
	v_pk_mul_f32 v[36:37], v[36:37], v[72:73]
	v_pk_mul_f32 v[34:35], v[34:35], v[70:71]
	s_waitcnt lgkmcnt(0)
	s_nop 0
	v_mfma_f32_16x16x32_bf16 v[34:37], v[126:129], v[66:69], v[34:37]
	ds_read_b128 v[70:73], v125 offset:57024
	ds_read_b64_tr_b16 v[126:127], v134 offset:27744
	ds_read_b64_tr_b16 v[128:129], v134 offset:32864
	s_waitcnt lgkmcnt(2)
	v_pk_mul_f32 v[40:41], v[40:41], v[72:73]
	v_pk_mul_f32 v[38:39], v[38:39], v[70:71]
	s_waitcnt lgkmcnt(0)
	s_nop 0
	v_mfma_f32_16x16x32_bf16 v[38:41], v[126:129], v[66:69], v[38:41]
	ds_read_b128 v[70:73], v125 offset:57088
	ds_read_b64_tr_b16 v[126:127], v134 offset:27776
	ds_read_b64_tr_b16 v[128:129], v134 offset:32896
	s_waitcnt lgkmcnt(2)
	v_pk_mul_f32 v[44:45], v[44:45], v[72:73]
	v_pk_mul_f32 v[42:43], v[42:43], v[70:71]
	s_waitcnt lgkmcnt(0)
	s_nop 0
	v_mfma_f32_16x16x32_bf16 v[42:45], v[126:129], v[66:69], v[42:45]
	ds_read_b128 v[70:73], v125 offset:57152
	ds_read_b64_tr_b16 v[126:127], v134 offset:27808
	ds_read_b64_tr_b16 v[128:129], v134 offset:32928
	s_waitcnt lgkmcnt(2)
	v_pk_mul_f32 v[48:49], v[48:49], v[72:73]
	v_pk_mul_f32 v[46:47], v[46:47], v[70:71]
	s_waitcnt lgkmcnt(0)
	s_nop 0
	v_mfma_f32_16x16x32_bf16 v[46:49], v[126:129], v[66:69], v[46:49]
	ds_read_b128 v[70:73], v125 offset:57216
	ds_read_b64_tr_b16 v[126:127], v134 offset:27840
	ds_read_b64_tr_b16 v[128:129], v134 offset:32960
	s_waitcnt lgkmcnt(2)
	v_pk_mul_f32 v[52:53], v[52:53], v[72:73]
	v_pk_mul_f32 v[50:51], v[50:51], v[70:71]
	s_waitcnt lgkmcnt(0)
	s_nop 0
	v_mfma_f32_16x16x32_bf16 v[50:53], v[126:129], v[66:69], v[50:53]
	ds_read_b128 v[70:73], v125 offset:57280
	ds_read_b64_tr_b16 v[126:127], v134 offset:27872
	ds_read_b64_tr_b16 v[128:129], v134 offset:32992
	s_waitcnt lgkmcnt(2)
	v_pk_mul_f32 v[56:57], v[56:57], v[72:73]
	v_pk_mul_f32 v[54:55], v[54:55], v[70:71]
	s_waitcnt lgkmcnt(0)
	s_nop 0
	v_mfma_f32_16x16x32_bf16 v[54:57], v[126:129], v[66:69], v[54:57]
	v_mul_f32_e32 v148, v62, v62
	v_mul_f32_e32 v149, v63, v63
	v_mul_f32_e32 v150, v64, v64
	v_mul_f32_e32 v151, v65, v65
	v_mul_f32_e32 v152, v58, v58
	v_mul_f32_e32 v153, v59, v59
	v_mul_f32_e32 v154, v60, v60
	v_mul_f32_e32 v155, v61, v61
	v_add_u32_e32 v156, s29, v112
	v_add_f32_dpp v148, v148, v148 row_ror:8 row_mask:0xf bank_mask:0xf bound_ctrl:1
	v_add_f32_dpp v149, v149, v149 row_ror:8 row_mask:0xf bank_mask:0xf bound_ctrl:1
	v_add_f32_dpp v150, v150, v150 row_ror:8 row_mask:0xf bank_mask:0xf bound_ctrl:1
	v_add_f32_dpp v151, v151, v151 row_ror:8 row_mask:0xf bank_mask:0xf bound_ctrl:1
	v_add_f32_dpp v152, v152, v152 row_ror:8 row_mask:0xf bank_mask:0xf bound_ctrl:1
	v_add_f32_dpp v153, v153, v153 row_ror:8 row_mask:0xf bank_mask:0xf bound_ctrl:1
	v_add_f32_dpp v154, v154, v154 row_ror:8 row_mask:0xf bank_mask:0xf bound_ctrl:1
	v_add_f32_dpp v155, v155, v155 row_ror:8 row_mask:0xf bank_mask:0xf bound_ctrl:1
	v_add_f32_dpp v148, v148, v148 row_ror:4 row_mask:0xf bank_mask:0xf bound_ctrl:1
	v_add_f32_dpp v149, v149, v149 row_ror:4 row_mask:0xf bank_mask:0xf bound_ctrl:1
	v_add_f32_dpp v150, v150, v150 row_ror:4 row_mask:0xf bank_mask:0xf bound_ctrl:1
	v_add_f32_dpp v151, v151, v151 row_ror:4 row_mask:0xf bank_mask:0xf bound_ctrl:1
	v_add_f32_dpp v152, v152, v152 row_ror:4 row_mask:0xf bank_mask:0xf bound_ctrl:1
	v_add_f32_dpp v153, v153, v153 row_ror:4 row_mask:0xf bank_mask:0xf bound_ctrl:1
	v_add_f32_dpp v154, v154, v154 row_ror:4 row_mask:0xf bank_mask:0xf bound_ctrl:1
	v_add_f32_dpp v155, v155, v155 row_ror:4 row_mask:0xf bank_mask:0xf bound_ctrl:1
	v_add_f32_dpp v148, v148, v148 row_ror:2 row_mask:0xf bank_mask:0xf bound_ctrl:1
	v_add_f32_dpp v149, v149, v149 row_ror:2 row_mask:0xf bank_mask:0xf bound_ctrl:1
	v_add_f32_dpp v150, v150, v150 row_ror:2 row_mask:0xf bank_mask:0xf bound_ctrl:1
	v_add_f32_dpp v151, v151, v151 row_ror:2 row_mask:0xf bank_mask:0xf bound_ctrl:1
	v_add_f32_dpp v152, v152, v152 row_ror:2 row_mask:0xf bank_mask:0xf bound_ctrl:1
	v_add_f32_dpp v153, v153, v153 row_ror:2 row_mask:0xf bank_mask:0xf bound_ctrl:1
	v_add_f32_dpp v154, v154, v154 row_ror:2 row_mask:0xf bank_mask:0xf bound_ctrl:1
	v_add_f32_dpp v155, v155, v155 row_ror:2 row_mask:0xf bank_mask:0xf bound_ctrl:1
	v_add_f32_dpp v148, v148, v148 row_ror:1 row_mask:0xf bank_mask:0xf bound_ctrl:1
	v_add_f32_dpp v149, v149, v149 row_ror:1 row_mask:0xf bank_mask:0xf bound_ctrl:1
	v_add_f32_dpp v150, v150, v150 row_ror:1 row_mask:0xf bank_mask:0xf bound_ctrl:1
	v_add_f32_dpp v151, v151, v151 row_ror:1 row_mask:0xf bank_mask:0xf bound_ctrl:1
	v_add_f32_dpp v152, v152, v152 row_ror:1 row_mask:0xf bank_mask:0xf bound_ctrl:1
	v_add_f32_dpp v153, v153, v153 row_ror:1 row_mask:0xf bank_mask:0xf bound_ctrl:1
	v_add_f32_dpp v154, v154, v154 row_ror:1 row_mask:0xf bank_mask:0xf bound_ctrl:1
	v_add_f32_dpp v155, v155, v155 row_ror:1 row_mask:0xf bank_mask:0xf bound_ctrl:1
	s_and_saveexec_b64 s[22:23], s[2:3]
	ds_write_b32 v156, v148 offset:57344
	ds_write_b32 v156, v149 offset:57376
	ds_write_b32 v156, v150 offset:57408
	ds_write_b32 v156, v151 offset:57440
	ds_write_b32 v156, v152 offset:57856
	ds_write_b32 v156, v153 offset:57888
	ds_write_b32 v156, v154 offset:57920
	ds_write_b32 v156, v155 offset:57952
	s_or_b64 exec, exec, s[22:23]
	s_waitcnt lgkmcnt(0)
	s_barrier
	s_andn2_b64 vcc, exec, s[20:21]
	s_cbranch_vccnz .LBB0_1330
	v_add3_u32 v68, s28, v96, v120
	v_add_u32_e32 v126, s28, v122
	ds_read_b64_tr_b16 v[66:67], v68 offset:17408
	ds_read_b64_tr_b16 v[68:69], v68 offset:18688
	v_add_u32_e32 v127, v126, v98
	v_add_u32_e32 v128, v126, v99
	ds_read_u16_d16_hi v180, v127 offset:17408
	ds_read_u16_d16_hi v181, v127 offset:17728
	ds_read_u16_d16_hi v182, v127 offset:18048
	ds_read_u16_d16_hi v183, v127 offset:18368
	ds_read_u16_d16_hi v184, v127 offset:22528
	ds_read_u16_d16_hi v185, v127 offset:22848
	ds_read_u16_d16_hi v186, v127 offset:23168
	ds_read_u16_d16_hi v187, v127 offset:23488
	ds_read_u16_d16_hi v188, v128 offset:0
	ds_read_u16_d16_hi v189, v128 offset:272
	ds_read_u16_d16_hi v190, v128 offset:544
	ds_read_u16_d16_hi v191, v128 offset:816
	s_waitcnt lgkmcnt(12)
	v_mfma_f32_16x16x32_bf16 v[70:73], v[4:7], v[66:69], 0
	v_mfma_f32_16x16x32_bf16 v[66:69], v[0:3], v[66:69], 0
	ds_read_u16_d16_hi v192, v128 offset:4352
	ds_read_u16_d16_hi v193, v128 offset:4624
	ds_read_u16_d16_hi v194, v128 offset:4896
	ds_read_u16_d16_hi v195, v128 offset:5168
	s_mov_b32 s23, 0x42e60000
	s_nop 2
	ds_bpermute_b32 v125, v121, v69
	v_exp_f32_e32 v196, v70
	v_exp_f32_e32 v197, v71
	v_exp_f32_e32 v198, v72
	v_exp_f32_e32 v199, v73
	v_min_f32_e64 v200, -v70, s23
	v_min_f32_e64 v201, -v71, s23
	v_min_f32_e64 v202, -v72, s23
	v_min_f32_e64 v203, -v73, s23
	v_exp_f32_e32 v200, v200
	v_exp_f32_e32 v201, v201
	v_exp_f32_e32 v202, v202
	v_exp_f32_e32 v203, v203
	s_waitcnt lgkmcnt(0)
	v_exp_f32_e32 v204, v180
	v_exp_f32_e32 v205, v181
	v_exp_f32_e32 v206, v182
	v_exp_f32_e32 v207, v183
	v_sub_f32_e32 v208, v125, v70
	v_sub_f32_e32 v209, v125, v71
	v_sub_f32_e32 v210, v125, v72
	v_sub_f32_e32 v211, v125, v73
	v_exp_f32_e32 v208, v208
	v_exp_f32_e32 v209, v209
	v_exp_f32_e32 v210, v210
	v_exp_f32_e32 v211, v211
	v_sub_f32_e32 v204, 1.0, v204
	v_sub_f32_e32 v205, 1.0, v205
	v_sub_f32_e32 v206, 1.0, v206
	v_sub_f32_e32 v207, 1.0, v207
	v_mul_f32_e32 v196, v196, v188
	v_mul_f32_e32 v197, v197, v189
	v_mul_f32_e32 v198, v198, v190
	v_mul_f32_e32 v199, v199, v191
	v_mul_f32_e32 v200, v200, v204
	v_mul_f32_e32 v201, v201, v205
	v_mul_f32_e32 v202, v202, v206
	v_mul_f32_e32 v203, v203, v207
	v_mul_f32_e32 v208, v208, v204
	v_mul_f32_e32 v209, v209, v205
	v_mul_f32_e32 v210, v210, v206
	v_mul_f32_e32 v211, v211, v207
	v_cvt_pk_bf16_f32 v212, v196, v197
	v_cvt_pk_bf16_f32 v214, v200, v201
	v_cvt_pk_bf16_f32 v216, v208, v209
	v_cvt_pk_bf16_f32 v213, v198, v199
	v_cvt_pk_bf16_f32 v215, v202, v203
	v_cvt_pk_bf16_f32 v217, v210, v211
	ds_write_b16 v128, v212 offset:0
	ds_write_b16_d16_hi v128, v212 offset:272
	ds_write_b16 v128, v214 offset:8704
	ds_write_b16_d16_hi v128, v214 offset:8976
	ds_write_b16 v127, v216 offset:27648
	ds_write_b16_d16_hi v127, v216 offset:27968
	ds_write_b16 v128, v213 offset:544
	ds_write_b16_d16_hi v128, v213 offset:816
	ds_write_b16 v128, v215 offset:9248
	ds_write_b16_d16_hi v128, v215 offset:9520
	ds_write_b16 v127, v217 offset:28288
	ds_write_b16_d16_hi v127, v217 offset:28608
	v_exp_f32_e32 v196, v66
	v_exp_f32_e32 v197, v67
	v_exp_f32_e32 v198, v68
	v_exp_f32_e32 v199, v69
	v_min_f32_e64 v200, -v66, s23
	v_min_f32_e64 v201, -v67, s23
	v_min_f32_e64 v202, -v68, s23
	v_min_f32_e64 v203, -v69, s23
	v_exp_f32_e32 v200, v200
	v_exp_f32_e32 v201, v201
	v_exp_f32_e32 v202, v202
	v_exp_f32_e32 v203, v203
	v_exp_f32_e32 v204, v184
	v_exp_f32_e32 v205, v185
	v_exp_f32_e32 v206, v186
	v_exp_f32_e32 v207, v187
	v_sub_f32_e32 v208, v125, v66
	v_sub_f32_e32 v209, v125, v67
	v_sub_f32_e32 v210, v125, v68
	v_sub_f32_e32 v211, v125, v69
	v_exp_f32_e32 v208, v208
	v_exp_f32_e32 v209, v209
	v_exp_f32_e32 v210, v210
	v_exp_f32_e32 v211, v211
	v_sub_f32_e32 v204, 1.0, v204
	v_sub_f32_e32 v205, 1.0, v205
	v_sub_f32_e32 v206, 1.0, v206
	v_sub_f32_e32 v207, 1.0, v207
	v_mul_f32_e32 v196, v196, v192
	v_mul_f32_e32 v197, v197, v193
	v_mul_f32_e32 v198, v198, v194
	v_mul_f32_e32 v199, v199, v195
	v_mul_f32_e32 v200, v200, v204
	v_mul_f32_e32 v201, v201, v205
	v_mul_f32_e32 v202, v202, v206
	v_mul_f32_e32 v203, v203, v207
	v_mul_f32_e32 v208, v208, v204
	v_mul_f32_e32 v209, v209, v205
	v_mul_f32_e32 v210, v210, v206
	v_mul_f32_e32 v211, v211, v207
	v_cvt_pk_bf16_f32 v212, v196, v197
	v_cvt_pk_bf16_f32 v214, v200, v201
	v_cvt_pk_bf16_f32 v216, v208, v209
	v_cvt_pk_bf16_f32 v213, v198, v199
	v_cvt_pk_bf16_f32 v215, v202, v203
	v_cvt_pk_bf16_f32 v217, v210, v211
	ds_write_b16 v128, v212 offset:4352
	ds_write_b16_d16_hi v128, v212 offset:4624
	ds_write_b16 v128, v214 offset:13056
	ds_write_b16_d16_hi v128, v214 offset:13328
	ds_write_b16 v127, v216 offset:32768
	ds_write_b16_d16_hi v127, v216 offset:33088
	ds_write_b16 v128, v213 offset:4896
	ds_write_b16_d16_hi v128, v213 offset:5168
	ds_write_b16 v128, v215 offset:13600
	ds_write_b16_d16_hi v128, v215 offset:13872
	ds_write_b16 v127, v217 offset:33408
	ds_write_b16_d16_hi v127, v217 offset:33728
	v_exp_f32_e32 v66, v125
	v_add_u32_e32 v67, s28, v124
	s_and_saveexec_b64 s[20:21], s[0:1]
	ds_write_b32 v67, v66 offset:56832
	s_branch .LBB0_1329
